# P4 GEMM K-loop: compiler-inserted per-iteration s_waitcnt vmcnt(0)/lgkmcnt(0) at the loop header hoisted in front of the loop (K-loop now uses only the template's counted vmcnt(8) like the other GEMM
# speedup vs baseline: 1.0186x; 1.0186x over previous
.LBB0_208:
	s_ashr_i32 s39, s38, 31
	s_lshl_b64 s[20:21], s[38:39], 19
	s_add_u32 s40, s52, s20
	s_addc_u32 s41, s53, s21
	s_and_b64 s[20:21], s[4:5], exec
	s_cselect_b32 s7, s41, s47
	s_cselect_b32 s10, s40, s46
	s_ashr_i32 s37, s36, 31
	s_lshl_b64 s[20:21], s[36:37], 19
	s_add_u32 s42, s54, s20
	s_addc_u32 s43, s55, s21
	s_and_b64 s[20:21], s[4:5], exec
	s_cselect_b32 s20, s43, s49
	s_cselect_b32 s21, s42, s48
	s_add_u32 s46, s46, 0x40080
	s_addc_u32 s47, s47, 0
	s_add_u32 s37, s48, 0x100
	v_mov_b32_e32 v2, 0
	s_addc_u32 s39, s49, 0
	s_mov_b32 s73, -2
	v_mov_b32_e32 v3, v2
	v_mov_b32_e32 v4, v2
	v_mov_b32_e32 v5, v2
	v_mov_b32_e32 v6, v2
	v_mov_b32_e32 v7, v2
	v_mov_b32_e32 v8, v2
	v_mov_b32_e32 v9, v2
	v_mov_b32_e32 v18, v2
	v_mov_b32_e32 v19, v2
	v_mov_b32_e32 v20, v2
	v_mov_b32_e32 v21, v2
	v_mov_b32_e32 v22, v2
	v_mov_b32_e32 v23, v2
	v_mov_b32_e32 v24, v2
	v_mov_b32_e32 v25, v2
	v_mov_b32_e32 v34, v2
	v_mov_b32_e32 v35, v2
	v_mov_b32_e32 v36, v2
	v_mov_b32_e32 v37, v2
	v_mov_b32_e32 v38, v2
	v_mov_b32_e32 v39, v2
	v_mov_b32_e32 v40, v2
	v_mov_b32_e32 v41, v2
	v_mov_b32_e32 v50, v2
	v_mov_b32_e32 v51, v2
	v_mov_b32_e32 v52, v2
	v_mov_b32_e32 v53, v2
	v_mov_b32_e32 v54, v2
	v_mov_b32_e32 v55, v2
	v_mov_b32_e32 v56, v2
	v_mov_b32_e32 v57, v2
	v_mov_b32_e32 v10, v2
	v_mov_b32_e32 v11, v2
	v_mov_b32_e32 v12, v2
	v_mov_b32_e32 v13, v2
	v_mov_b32_e32 v14, v2
	v_mov_b32_e32 v15, v2
	v_mov_b32_e32 v16, v2
	v_mov_b32_e32 v17, v2
	v_mov_b32_e32 v26, v2
	v_mov_b32_e32 v27, v2
	v_mov_b32_e32 v28, v2
	v_mov_b32_e32 v29, v2
	v_mov_b32_e32 v30, v2
	v_mov_b32_e32 v31, v2
	v_mov_b32_e32 v32, v2
	v_mov_b32_e32 v33, v2
	v_mov_b32_e32 v42, v2
	v_mov_b32_e32 v43, v2
	v_mov_b32_e32 v44, v2
	v_mov_b32_e32 v45, v2
	v_mov_b32_e32 v46, v2
	v_mov_b32_e32 v47, v2
	v_mov_b32_e32 v48, v2
	v_mov_b32_e32 v49, v2
	v_mov_b32_e32 v58, v2
	v_mov_b32_e32 v59, v2
	v_mov_b32_e32 v60, v2
	v_mov_b32_e32 v61, v2
	v_mov_b32_e32 v62, v2
	v_mov_b32_e32 v63, v2
	v_mov_b32_e32 v64, v2
	v_mov_b32_e32 v65, v2
	v_mov_b32_e32 v66, v2
	v_mov_b32_e32 v67, v2
	v_mov_b32_e32 v68, v2
	v_mov_b32_e32 v69, v2
	v_mov_b32_e32 v70, v2
	v_mov_b32_e32 v71, v2
	v_mov_b32_e32 v72, v2
	v_mov_b32_e32 v73, v2
	v_mov_b32_e32 v82, v2
	v_mov_b32_e32 v83, v2
	v_mov_b32_e32 v84, v2
	v_mov_b32_e32 v85, v2
	v_mov_b32_e32 v86, v2
	v_mov_b32_e32 v87, v2
	v_mov_b32_e32 v88, v2
	v_mov_b32_e32 v89, v2
	v_mov_b32_e32 v98, v2
	v_mov_b32_e32 v99, v2
	v_mov_b32_e32 v100, v2
	v_mov_b32_e32 v101, v2
	v_mov_b32_e32 v102, v2
	v_mov_b32_e32 v103, v2
	v_mov_b32_e32 v104, v2
	v_mov_b32_e32 v105, v2
	v_mov_b32_e32 v114, v2
	v_mov_b32_e32 v115, v2
	v_mov_b32_e32 v116, v2
	v_mov_b32_e32 v117, v2
	v_mov_b32_e32 v118, v2
	v_mov_b32_e32 v119, v2
	v_mov_b32_e32 v120, v2
	v_mov_b32_e32 v121, v2
	v_mov_b32_e32 v74, v2
	v_mov_b32_e32 v75, v2
	v_mov_b32_e32 v76, v2
	v_mov_b32_e32 v77, v2
	v_mov_b32_e32 v78, v2
	v_mov_b32_e32 v79, v2
	v_mov_b32_e32 v80, v2
	v_mov_b32_e32 v81, v2
	v_mov_b32_e32 v90, v2
	v_mov_b32_e32 v91, v2
	v_mov_b32_e32 v92, v2
	v_mov_b32_e32 v93, v2
	v_mov_b32_e32 v94, v2
	v_mov_b32_e32 v95, v2
	v_mov_b32_e32 v96, v2
	v_mov_b32_e32 v97, v2
	v_mov_b32_e32 v106, v2
	v_mov_b32_e32 v107, v2
	v_mov_b32_e32 v108, v2
	v_mov_b32_e32 v109, v2
	v_mov_b32_e32 v110, v2
	v_mov_b32_e32 v111, v2
	v_mov_b32_e32 v112, v2
	v_mov_b32_e32 v113, v2
	v_mov_b32_e32 v122, v2
	v_mov_b32_e32 v123, v2
	v_mov_b32_e32 v124, v2
	v_mov_b32_e32 v125, v2
	v_mov_b32_e32 v126, v2
	v_mov_b32_e32 v127, v2
	v_mov_b32_e32 v128, v2
	v_mov_b32_e32 v129, v2
	s_waitcnt vmcnt(0) lgkmcnt(0)
.LBB0_209:
	ds_read_b128 v[130:133], v197
	ds_read_b128 v[134:137], v197 offset:1024
	ds_read_b128 v[138:141], v197 offset:2048
	ds_read_b128 v[142:145], v197 offset:3072
	ds_read_b128 v[146:149], v198
	ds_read_b128 v[150:153], v198 offset:1024
	ds_read_b128 v[176:179], v198 offset:2048
	ds_read_b128 v[180:183], v198 offset:3072
	s_add_u32 s48, s46, 0xfffc0080
	s_addc_u32 s49, s47, -1
	s_cmp_eq_u32 s73, 12
	s_cselect_b32 s51, s7, s49
	s_cselect_b32 s50, s10, s48
	s_cselect_b32 s49, s20, s39
	s_cselect_b32 s48, s21, s37
	v_lshl_add_u64 v[192:193], s[46:47], 0, v[168:169]
	s_add_i32 m0, s45, 0xc000
	ds_read_b128 v[184:187], v199
	ds_read_b128 v[188:191], v199 offset:1024
	ds_read_b128 v[202:205], v199 offset:2048
	ds_read_b128 v[206:209], v199 offset:3072
	ds_read_b128 v[210:213], v199 offset:4096
	ds_read_b128 v[214:217], v199 offset:5120
	ds_read_b128 v[218:221], v199 offset:6144
	ds_read_b128 v[222:225], v199 offset:7168
	global_load_lds_dwordx4 v[192:193], off
	v_lshl_add_u64 v[192:193], s[46:47], 0, v[170:171]
	s_add_i32 m0, s45, 0xe000
	s_nop 0
	global_load_lds_dwordx4 v[192:193], off
	s_waitcnt vmcnt(8)
	s_waitcnt lgkmcnt(0)
	s_barrier
	s_setprio 1
	s_waitcnt lgkmcnt(0)
	v_mfma_f32_16x16x32_bf16 v[126:129], v[130:133], v[184:187], v[126:129]
	v_mfma_f32_16x16x32_bf16 v[122:125], v[138:141], v[184:187], v[122:125]
	v_mfma_f32_16x16x32_bf16 v[110:113], v[130:133], v[202:205], v[110:113]
	v_mfma_f32_16x16x32_bf16 v[106:109], v[138:141], v[202:205], v[106:109]
	v_mfma_f32_16x16x32_bf16 v[94:97], v[130:133], v[210:213], v[94:97]
	v_mfma_f32_16x16x32_bf16 v[90:93], v[138:141], v[210:213], v[90:93]
	v_mfma_f32_16x16x32_bf16 v[78:81], v[130:133], v[218:221], v[78:81]
	v_mfma_f32_16x16x32_bf16 v[74:77], v[138:141], v[218:221], v[74:77]
	v_mfma_f32_16x16x32_bf16 v[126:129], v[134:137], v[188:191], v[126:129]
	v_mfma_f32_16x16x32_bf16 v[122:125], v[142:145], v[188:191], v[122:125]
	v_mfma_f32_16x16x32_bf16 v[110:113], v[134:137], v[206:209], v[110:113]
	v_mfma_f32_16x16x32_bf16 v[106:109], v[142:145], v[206:209], v[106:109]
	v_mfma_f32_16x16x32_bf16 v[94:97], v[134:137], v[214:217], v[94:97]
	v_mfma_f32_16x16x32_bf16 v[90:93], v[142:145], v[214:217], v[90:93]
	v_mfma_f32_16x16x32_bf16 v[78:81], v[134:137], v[222:225], v[78:81]
	v_mfma_f32_16x16x32_bf16 v[74:77], v[142:145], v[222:225], v[74:77]
	s_setprio 0
	s_setprio 1
	v_mfma_f32_16x16x32_bf16 v[118:121], v[146:149], v[184:187], v[118:121]
	v_mfma_f32_16x16x32_bf16 v[114:117], v[176:179], v[184:187], v[114:117]
	v_mfma_f32_16x16x32_bf16 v[102:105], v[146:149], v[202:205], v[102:105]
	v_mfma_f32_16x16x32_bf16 v[98:101], v[176:179], v[202:205], v[98:101]
	v_mfma_f32_16x16x32_bf16 v[86:89], v[146:149], v[210:213], v[86:89]
	v_mfma_f32_16x16x32_bf16 v[82:85], v[176:179], v[210:213], v[82:85]
	v_mfma_f32_16x16x32_bf16 v[70:73], v[146:149], v[218:221], v[70:73]
	v_mfma_f32_16x16x32_bf16 v[66:69], v[176:179], v[218:221], v[66:69]
	v_mfma_f32_16x16x32_bf16 v[118:121], v[150:153], v[188:191], v[118:121]
	v_mfma_f32_16x16x32_bf16 v[114:117], v[180:183], v[188:191], v[114:117]
	v_mfma_f32_16x16x32_bf16 v[102:105], v[150:153], v[206:209], v[102:105]
	v_mfma_f32_16x16x32_bf16 v[98:101], v[180:183], v[206:209], v[98:101]
	v_mfma_f32_16x16x32_bf16 v[86:89], v[150:153], v[214:217], v[86:89]
	v_mfma_f32_16x16x32_bf16 v[82:85], v[180:183], v[214:217], v[82:85]
	v_mfma_f32_16x16x32_bf16 v[70:73], v[150:153], v[222:225], v[70:73]
	v_mfma_f32_16x16x32_bf16 v[66:69], v[180:183], v[222:225], v[66:69]
	s_setprio 0
	s_barrier
	s_add_i32 s74, s66, s56
	v_lshl_add_u64 v[192:193], s[48:49], 0, v[156:157]
	s_mov_b32 m0, s74
	ds_read_b128 v[184:187], v199 offset:16384
	ds_read_b128 v[188:191], v199 offset:17408
	ds_read_b128 v[202:205], v199 offset:18432
	ds_read_b128 v[206:209], v199 offset:19456
	ds_read_b128 v[210:213], v199 offset:20480
	ds_read_b128 v[214:217], v199 offset:21504
	ds_read_b128 v[218:221], v199 offset:22528
	ds_read_b128 v[222:225], v199 offset:23552
	global_load_lds_dwordx4 v[192:193], off
	s_add_i32 m0, s74, 0x2000
	s_add_u32 s74, s48, 0x40000
	v_lshl_add_u64 v[226:227], s[48:49], 0, v[160:161]
	s_addc_u32 s75, s49, 0
	s_add_i32 s76, s67, s56
	global_load_lds_dwordx4 v[226:227], off
	v_lshl_add_u64 v[228:229], s[74:75], 0, v[156:157]
	s_mov_b32 m0, s76
	v_lshl_add_u64 v[230:231], s[50:51], 0, v[158:159]
	global_load_lds_dwordx4 v[228:229], off
	v_lshl_add_u64 v[228:229], s[74:75], 0, v[160:161]
	s_add_i32 m0, s76, 0x2000
	s_nop 0
	global_load_lds_dwordx4 v[228:229], off
	v_lshl_add_u64 v[228:229], s[50:51], 0, v[154:155]
	s_mov_b32 m0, s45
	s_nop 0
	global_load_lds_dwordx4 v[228:229], off
	s_mov_b32 m0, s57
	s_nop 0
	global_load_lds_dwordx4 v[230:231], off
	s_waitcnt vmcnt(8)
	s_waitcnt lgkmcnt(0)
	s_barrier
	s_setprio 1
	s_waitcnt lgkmcnt(0)
	v_mfma_f32_16x16x32_bf16 v[62:65], v[130:133], v[184:187], v[62:65]
	v_mfma_f32_16x16x32_bf16 v[58:61], v[138:141], v[184:187], v[58:61]
	v_mfma_f32_16x16x32_bf16 v[46:49], v[130:133], v[202:205], v[46:49]
	v_mfma_f32_16x16x32_bf16 v[42:45], v[138:141], v[202:205], v[42:45]
	v_mfma_f32_16x16x32_bf16 v[30:33], v[130:133], v[210:213], v[30:33]
	v_mfma_f32_16x16x32_bf16 v[26:29], v[138:141], v[210:213], v[26:29]
	v_mfma_f32_16x16x32_bf16 v[14:17], v[130:133], v[218:221], v[14:17]
	v_mfma_f32_16x16x32_bf16 v[10:13], v[138:141], v[218:221], v[10:13]
	v_mfma_f32_16x16x32_bf16 v[62:65], v[134:137], v[188:191], v[62:65]
	v_mfma_f32_16x16x32_bf16 v[58:61], v[142:145], v[188:191], v[58:61]
	v_mfma_f32_16x16x32_bf16 v[46:49], v[134:137], v[206:209], v[46:49]
	v_mfma_f32_16x16x32_bf16 v[42:45], v[142:145], v[206:209], v[42:45]
	v_mfma_f32_16x16x32_bf16 v[30:33], v[134:137], v[214:217], v[30:33]
	v_mfma_f32_16x16x32_bf16 v[26:29], v[142:145], v[214:217], v[26:29]
	v_mfma_f32_16x16x32_bf16 v[14:17], v[134:137], v[222:225], v[14:17]
	v_mfma_f32_16x16x32_bf16 v[10:13], v[142:145], v[222:225], v[10:13]
	s_setprio 0
	s_setprio 1
	v_mfma_f32_16x16x32_bf16 v[54:57], v[146:149], v[184:187], v[54:57]
	v_mfma_f32_16x16x32_bf16 v[50:53], v[176:179], v[184:187], v[50:53]
	v_mfma_f32_16x16x32_bf16 v[38:41], v[146:149], v[202:205], v[38:41]
	v_mfma_f32_16x16x32_bf16 v[34:37], v[176:179], v[202:205], v[34:37]
	v_mfma_f32_16x16x32_bf16 v[22:25], v[146:149], v[210:213], v[22:25]
	v_mfma_f32_16x16x32_bf16 v[18:21], v[176:179], v[210:213], v[18:21]
	v_mfma_f32_16x16x32_bf16 v[6:9], v[146:149], v[218:221], v[6:9]
	v_mfma_f32_16x16x32_bf16 v[2:5], v[176:179], v[218:221], v[2:5]
	v_mfma_f32_16x16x32_bf16 v[54:57], v[150:153], v[188:191], v[54:57]
	v_mfma_f32_16x16x32_bf16 v[50:53], v[180:183], v[188:191], v[50:53]
	v_mfma_f32_16x16x32_bf16 v[38:41], v[150:153], v[206:209], v[38:41]
	v_mfma_f32_16x16x32_bf16 v[34:37], v[180:183], v[206:209], v[34:37]
	v_mfma_f32_16x16x32_bf16 v[22:25], v[150:153], v[214:217], v[22:25]
	v_mfma_f32_16x16x32_bf16 v[18:21], v[180:183], v[214:217], v[18:21]
	v_mfma_f32_16x16x32_bf16 v[6:9], v[150:153], v[222:225], v[6:9]
	v_mfma_f32_16x16x32_bf16 v[2:5], v[180:183], v[222:225], v[2:5]
	s_setprio 0
	s_barrier
	s_add_i32 s74, 0, 0x18000
	s_add_i32 s75, 0, 0x1c000
	v_add_u32_e32 v142, s74, v194
	v_add_u32_e32 v162, s75, v194
	ds_read_b128 v[130:133], v142
	ds_read_b128 v[134:137], v142 offset:1024
	ds_read_b128 v[138:141], v142 offset:2048
	ds_read_b128 v[142:145], v142 offset:3072
	ds_read_b128 v[146:149], v162
	ds_read_b128 v[150:153], v162 offset:1024
	ds_read_b128 v[176:179], v162 offset:2048
	ds_read_b128 v[180:183], v162 offset:3072
	s_add_u32 s50, s50, 0x40000
	s_addc_u32 s51, s51, 0
	s_mov_b32 m0, s58
	v_lshl_add_u64 v[232:233], s[50:51], 0, v[154:155]
	ds_read_b128 v[184:187], v199 offset:32768
	ds_read_b128 v[188:191], v199 offset:33792
	ds_read_b128 v[202:205], v199 offset:34816
	ds_read_b128 v[206:209], v199 offset:35840
	ds_read_b128 v[210:213], v199 offset:36864
	ds_read_b128 v[214:217], v199 offset:37888
	ds_read_b128 v[218:221], v199 offset:38912
	ds_read_b128 v[222:225], v199 offset:39936
	global_load_lds_dwordx4 v[232:233], off
	v_lshl_add_u64 v[232:233], s[50:51], 0, v[158:159]
	s_mov_b32 m0, s59
	s_nop 0
	global_load_lds_dwordx4 v[232:233], off
	s_waitcnt vmcnt(8)
	s_waitcnt lgkmcnt(0)
	s_barrier
	s_setprio 1
	s_waitcnt lgkmcnt(0)
	v_mfma_f32_16x16x32_bf16 v[126:129], v[130:133], v[184:187], v[126:129]
	v_mfma_f32_16x16x32_bf16 v[122:125], v[138:141], v[184:187], v[122:125]
	v_mfma_f32_16x16x32_bf16 v[110:113], v[130:133], v[202:205], v[110:113]
	v_mfma_f32_16x16x32_bf16 v[106:109], v[138:141], v[202:205], v[106:109]
	v_mfma_f32_16x16x32_bf16 v[94:97], v[130:133], v[210:213], v[94:97]
	v_mfma_f32_16x16x32_bf16 v[90:93], v[138:141], v[210:213], v[90:93]
	v_mfma_f32_16x16x32_bf16 v[78:81], v[130:133], v[218:221], v[78:81]
	v_mfma_f32_16x16x32_bf16 v[74:77], v[138:141], v[218:221], v[74:77]
	v_mfma_f32_16x16x32_bf16 v[126:129], v[134:137], v[188:191], v[126:129]
	v_mfma_f32_16x16x32_bf16 v[122:125], v[142:145], v[188:191], v[122:125]
	v_mfma_f32_16x16x32_bf16 v[110:113], v[134:137], v[206:209], v[110:113]
	v_mfma_f32_16x16x32_bf16 v[106:109], v[142:145], v[206:209], v[106:109]
	v_mfma_f32_16x16x32_bf16 v[94:97], v[134:137], v[214:217], v[94:97]
	v_mfma_f32_16x16x32_bf16 v[90:93], v[142:145], v[214:217], v[90:93]
	v_mfma_f32_16x16x32_bf16 v[78:81], v[134:137], v[222:225], v[78:81]
	v_mfma_f32_16x16x32_bf16 v[74:77], v[142:145], v[222:225], v[74:77]
	s_setprio 0
	s_setprio 1
	v_mfma_f32_16x16x32_bf16 v[118:121], v[146:149], v[184:187], v[118:121]
	v_mfma_f32_16x16x32_bf16 v[114:117], v[176:179], v[184:187], v[114:117]
	v_mfma_f32_16x16x32_bf16 v[102:105], v[146:149], v[202:205], v[102:105]
	v_mfma_f32_16x16x32_bf16 v[98:101], v[176:179], v[202:205], v[98:101]
	v_mfma_f32_16x16x32_bf16 v[86:89], v[146:149], v[210:213], v[86:89]
	v_mfma_f32_16x16x32_bf16 v[82:85], v[176:179], v[210:213], v[82:85]
	v_mfma_f32_16x16x32_bf16 v[70:73], v[146:149], v[218:221], v[70:73]
	v_mfma_f32_16x16x32_bf16 v[66:69], v[176:179], v[218:221], v[66:69]
	v_mfma_f32_16x16x32_bf16 v[118:121], v[150:153], v[188:191], v[118:121]
	v_mfma_f32_16x16x32_bf16 v[114:117], v[180:183], v[188:191], v[114:117]
	v_mfma_f32_16x16x32_bf16 v[102:105], v[150:153], v[206:209], v[102:105]
	v_mfma_f32_16x16x32_bf16 v[98:101], v[180:183], v[206:209], v[98:101]
	v_mfma_f32_16x16x32_bf16 v[86:89], v[150:153], v[214:217], v[86:89]
	v_mfma_f32_16x16x32_bf16 v[82:85], v[180:183], v[214:217], v[82:85]
	v_mfma_f32_16x16x32_bf16 v[70:73], v[150:153], v[222:225], v[70:73]
	v_mfma_f32_16x16x32_bf16 v[66:69], v[180:183], v[222:225], v[66:69]
	s_setprio 0
	s_barrier
	s_add_i32 s50, s74, s56
	v_lshl_add_u64 v[192:193], v[192:193], 0, s[18:19]
	s_mov_b32 m0, s50
	ds_read_b128 v[184:187], v199 offset:49152
	ds_read_b128 v[188:191], v199 offset:50176
	ds_read_b128 v[202:205], v199 offset:51200
	ds_read_b128 v[206:209], v199 offset:52224
	ds_read_b128 v[210:213], v199 offset:53248
	ds_read_b128 v[214:217], v199 offset:54272
	ds_read_b128 v[218:221], v199 offset:55296
	ds_read_b128 v[222:225], v199 offset:56320
	global_load_lds_dwordx4 v[192:193], off
	s_add_i32 m0, s50, 0x2000
	s_add_u32 s48, s48, 0x40080
	v_lshl_add_u64 v[192:193], v[226:227], 0, s[18:19]
	s_addc_u32 s49, s49, 0
	s_add_i32 s50, s75, s56
	global_load_lds_dwordx4 v[192:193], off
	v_lshl_add_u64 v[192:193], s[48:49], 0, v[156:157]
	s_mov_b32 m0, s50
	s_nop 0
	global_load_lds_dwordx4 v[192:193], off
	v_lshl_add_u64 v[192:193], s[48:49], 0, v[160:161]
	s_add_i32 m0, s50, 0x2000
	s_nop 0
	global_load_lds_dwordx4 v[192:193], off
	v_lshl_add_u64 v[192:193], v[228:229], 0, s[18:19]
	s_mov_b32 m0, s61
	s_nop 0
	global_load_lds_dwordx4 v[192:193], off
	v_lshl_add_u64 v[192:193], v[230:231], 0, s[18:19]
	s_mov_b32 m0, s62
	s_nop 0
	global_load_lds_dwordx4 v[192:193], off
	s_waitcnt vmcnt(8)
	s_waitcnt lgkmcnt(0)
	s_barrier
	s_setprio 1
	s_waitcnt lgkmcnt(0)
	v_mfma_f32_16x16x32_bf16 v[62:65], v[130:133], v[184:187], v[62:65]
	v_mfma_f32_16x16x32_bf16 v[58:61], v[138:141], v[184:187], v[58:61]
	v_mfma_f32_16x16x32_bf16 v[46:49], v[130:133], v[202:205], v[46:49]
	v_mfma_f32_16x16x32_bf16 v[42:45], v[138:141], v[202:205], v[42:45]
	v_mfma_f32_16x16x32_bf16 v[30:33], v[130:133], v[210:213], v[30:33]
	v_mfma_f32_16x16x32_bf16 v[26:29], v[138:141], v[210:213], v[26:29]
	v_mfma_f32_16x16x32_bf16 v[14:17], v[130:133], v[218:221], v[14:17]
	v_mfma_f32_16x16x32_bf16 v[10:13], v[138:141], v[218:221], v[10:13]
	v_mfma_f32_16x16x32_bf16 v[62:65], v[134:137], v[188:191], v[62:65]
	v_mfma_f32_16x16x32_bf16 v[58:61], v[142:145], v[188:191], v[58:61]
	v_mfma_f32_16x16x32_bf16 v[46:49], v[134:137], v[206:209], v[46:49]
	v_mfma_f32_16x16x32_bf16 v[42:45], v[142:145], v[206:209], v[42:45]
	v_mfma_f32_16x16x32_bf16 v[30:33], v[134:137], v[214:217], v[30:33]
	v_mfma_f32_16x16x32_bf16 v[26:29], v[142:145], v[214:217], v[26:29]
	v_mfma_f32_16x16x32_bf16 v[14:17], v[134:137], v[222:225], v[14:17]
	v_mfma_f32_16x16x32_bf16 v[10:13], v[142:145], v[222:225], v[10:13]
	s_setprio 0
	s_setprio 1
	v_mfma_f32_16x16x32_bf16 v[54:57], v[146:149], v[184:187], v[54:57]
	v_mfma_f32_16x16x32_bf16 v[50:53], v[176:179], v[184:187], v[50:53]
	v_mfma_f32_16x16x32_bf16 v[38:41], v[146:149], v[202:205], v[38:41]
	v_mfma_f32_16x16x32_bf16 v[34:37], v[176:179], v[202:205], v[34:37]
	v_mfma_f32_16x16x32_bf16 v[22:25], v[146:149], v[210:213], v[22:25]
	v_mfma_f32_16x16x32_bf16 v[18:21], v[176:179], v[210:213], v[18:21]
	v_mfma_f32_16x16x32_bf16 v[6:9], v[146:149], v[218:221], v[6:9]
	v_mfma_f32_16x16x32_bf16 v[2:5], v[176:179], v[218:221], v[2:5]
	v_mfma_f32_16x16x32_bf16 v[54:57], v[150:153], v[188:191], v[54:57]
	v_mfma_f32_16x16x32_bf16 v[50:53], v[180:183], v[188:191], v[50:53]
	v_mfma_f32_16x16x32_bf16 v[38:41], v[150:153], v[206:209], v[38:41]
	v_mfma_f32_16x16x32_bf16 v[34:37], v[180:183], v[206:209], v[34:37]
	v_mfma_f32_16x16x32_bf16 v[22:25], v[150:153], v[214:217], v[22:25]
	v_mfma_f32_16x16x32_bf16 v[18:21], v[180:183], v[214:217], v[18:21]
	v_mfma_f32_16x16x32_bf16 v[6:9], v[150:153], v[222:225], v[6:9]
	v_mfma_f32_16x16x32_bf16 v[2:5], v[180:183], v[222:225], v[2:5]
	s_setprio 0
	s_barrier
	s_add_i32 s73, s73, 2
	s_add_u32 s46, s46, 0x100
	s_addc_u32 s47, s47, 0
	s_add_u32 s37, s37, 0x100
	s_addc_u32 s39, s39, 0
	s_cmp_gt_u32 s73, 13
	s_cbranch_scc0 .LBB0_209
	s_and_b64 vcc, exec, s[22:23]
	s_cbranch_vccz .LBB0_212
	s_barrier
